# gswap:10 instead of gswap:11 on the la_lb2 stack: NSA head group flips every 4 units (finer mix of the two head groups per workgroup)
# speedup vs baseline: 1.0054x; 1.0027x over previous
.LBB0_1007:
	s_mov_b32 s90, s20
	s_lshl_b32 s0, s23, 13
	s_lshl_b32 s1, s20, 4
	s_and_b32 s40, s22, 3
	s_bfe_u32 s29, s22, 0x10002
	s_bfe_u32 s98, s22, 0x1000a
	s_xor_b32 s29, s29, s98
	s_lshl_b32 s74, s75, 4
	s_and_b32 s0, s0, 0x6000
	s_ashr_i32 s20, s1, 31
	s_add_u32 s0, s1, s0
	s_addc_u32 s1, s20, 0
	v_or_b32_e32 v0, s0, v130
	s_lshl_b32 s0, s23, 1
	v_mov_b32_e32 v1, s1
	s_and_b32 s0, s0, 8
	s_lshr_b32 s98, s23, 7
	s_and_b32 s98, s98, 8
	s_xor_b32 s0, s0, s98
	v_add_u32_e32 v4, s0, v131
	v_lshlrev_b64 v[0:1], 12, v[0:1]
	v_lshl_add_u64 v[0:1], s[36:37], 0, v[0:1]
	v_lshlrev_b32_e32 v2, 7, v4
	v_mov_b32_e32 v3, v123
	v_lshl_add_u64 v[2:3], v[0:1], 0, v[2:3]
	v_mov_b32_e32 v133, v123
	v_lshl_add_u64 v[2:3], v[2:3], 0, v[132:133]
	global_load_dwordx4 v[48:51], v[2:3], off
	global_load_dwordx4 v[52:55], v[2:3], off offset:64
	v_mul_u32_u24_e32 v2, 3, v4
	v_lshlrev_b32_e32 v2, 1, v2
	v_mov_b32_e32 v3, v123
	v_lshl_add_u64 v[0:1], v[0:1], 0, v[2:3]
	global_load_dword v133, v[0:1], off offset:3584
	global_load_ushort v185, v[0:1], off offset:3588
	v_lshl_add_u32 v184, s29, 3, v131
	v_add_u32_e32 v0, 1, v184
	v_cvt_f32_ubyte0_e32 v0, v0
	v_mul_f32_e32 v1, -0.5, v0
	v_cmp_gt_f32_e32 vcc, s64, v1
	s_lshl_b32 s0, s40, 1
	s_or_b32 s47, s0, s29
	v_cndmask_b32_e32 v1, 0, v177, vcc
	v_fmac_f32_e32 v1, -0.5, v0
	v_exp_f32_e32 v0, v1
	s_add_i32 s0, s75, -1
	s_ashr_i32 s0, s0, 6
	s_add_i32 s0, s0, 1
	v_cndmask_b32_e32 v1, 0, v178, vcc
	s_cmp_gt_i32 s75, 0
	v_ldexp_f32 v0, v0, v1
	s_cselect_b32 s20, s0, 0
	v_mov_b32_e32 v75, 0
	v_mul_f32_e32 v146, 0x3fb8aa3b, v0
	v_or_b32_e32 v144, s74, v130
	s_cmp_lt_i32 s20, 1
	v_add_u32_e32 v187, 0xa000, v152
	v_add_u32_e32 v186, 0xc800, v152
	v_mov_b32_e32 v74, 0
	v_mov_b32_e32 v73, 0
	v_mov_b32_e32 v72, 0
	v_mov_b32_e32 v79, 0
	v_mov_b32_e32 v78, 0
	v_mov_b32_e32 v77, 0
	v_mov_b32_e32 v76, 0
	v_mov_b32_e32 v71, 0
	v_mov_b32_e32 v70, 0
	v_mov_b32_e32 v69, 0
	v_mov_b32_e32 v68, 0
	v_mov_b32_e32 v67, 0
	v_mov_b32_e32 v66, 0
	v_mov_b32_e32 v65, 0
	v_mov_b32_e32 v64, 0
	v_mov_b32_e32 v80, 0
	v_mov_b32_e32 v81, 0
	s_cbranch_scc1 .LBB0_1027
	s_lshl_b32 s21, s47, 16
	s_add_u32 s0, s3, s21
	s_addc_u32 s1, s52, 0
	s_add_u32 s22, s53, s21
	s_addc_u32 s23, s54, 0
	s_add_i32 s21, s20, -1
	s_cmp_eq_u32 s20, 1
	s_cselect_b64 s[24:25], -1, 0
	s_and_b64 vcc, s[24:25], exec
	s_cselect_b32 s26, 0, 64
	s_lshl_b32 s24, s26, 7
	v_mov_b32_e32 v135, v123
	s_add_u32 s24, s0, s24
	v_lshl_add_u64 v[0:1], s[0:1], 0, v[134:135]
	v_mov_b32_e32 v137, v123
	s_addc_u32 s25, s1, 0
	s_lshl_b32 s26, s26, 1
	v_lshl_add_u64 v[44:45], v[0:1], 0, v[122:123]
	v_lshl_add_u64 v[0:1], s[22:23], 0, v[136:137]
	s_add_u32 s26, s22, s26
	v_lshl_add_u64 v[46:47], v[0:1], 0, v[122:123]
	s_addc_u32 s27, s23, 0
	v_lshl_add_u64 v[0:1], s[24:25], 0, v[134:135]
	v_mov_b32_e32 v8, v240
	v_mov_b32_e32 v9, v241
	v_mov_b32_e32 v10, v242
	v_mov_b32_e32 v11, v243
	v_mov_b32_e32 v12, v244
	v_mov_b32_e32 v13, v245
	v_mov_b32_e32 v14, v246
	v_mov_b32_e32 v15, v247
	v_lshl_add_u64 v[0:1], v[0:1], 0, v[122:123]
	v_lshl_add_u64 v[2:3], s[26:27], 0, v[136:137]
	v_lshl_add_u64 v[2:3], v[2:3], 0, v[122:123]
	v_mov_b32_e32 v16, v248
	v_mov_b32_e32 v17, v249
	v_mov_b32_e32 v18, v250
	v_mov_b32_e32 v19, v251
	v_mov_b32_e32 v20, v252
	v_mov_b32_e32 v21, v253
	v_mov_b32_e32 v22, v254
	v_mov_b32_e32 v23, v255
	s_min_u32 s26, s21, 2
	s_lshl_b32 s24, s26, 13
	s_add_u32 s24, s0, s24
	s_addc_u32 s25, s1, 0
	s_lshl_b32 s26, s26, 7
	s_add_u32 s26, s22, s26
	v_lshl_add_u64 v[0:1], s[24:25], 0, v[134:135]
	s_addc_u32 s27, s23, 0
	s_min_u32 s24, s21, 3
	s_lshl_b32 s25, s24, 13
	s_add_u32 s0, s0, s25
	v_lshl_add_u64 v[2:3], s[26:27], 0, v[136:137]
	s_addc_u32 s1, s1, 0
	s_lshl_b32 s24, s24, 7
	v_lshl_add_u64 v[0:1], v[0:1], 0, v[122:123]
	v_lshl_add_u64 v[2:3], v[2:3], 0, v[122:123]
	s_add_u32 s22, s22, s24
	global_load_dwordx4 v[4:7], v[0:1], off
	s_nop 0
	global_load_dwordx4 v[0:3], v[2:3], off
	v_lshl_add_u64 v[24:25], s[0:1], 0, v[134:135]
	s_addc_u32 s23, s23, 0
	v_lshl_add_u64 v[24:25], v[24:25], 0, v[122:123]
	v_lshl_add_u64 v[26:27], s[22:23], 0, v[136:137]
	v_lshl_add_u64 v[26:27], v[26:27], 0, v[122:123]
	v_mov_b32_e32 v75, 0
	s_mov_b32 s0, 0
	v_mov_b32_e32 v74, v75
	v_mov_b32_e32 v73, v75
	v_mov_b32_e32 v72, v75
	v_mov_b32_e32 v79, v75
	v_mov_b32_e32 v78, v75
	v_mov_b32_e32 v77, v75
	v_mov_b32_e32 v76, v75
	v_mov_b32_e32 v71, v75
	v_mov_b32_e32 v70, v75
	v_mov_b32_e32 v69, v75
	v_mov_b32_e32 v68, v75
	v_mov_b32_e32 v67, v75
	v_mov_b32_e32 v66, v75
	v_mov_b32_e32 v65, v75
	v_mov_b32_e32 v64, v75
	v_mov_b32_e32 v80, v75
	v_mov_b32_e32 v81, v75
	ds_write_b128 v151, v[8:11]
	ds_write2_b64 v187, v[12:13], v[14:15] offset1:2
	ds_write_b128 v151, v[16:19] offset:10240
	ds_write2_b64 v186, v[20:21], v[22:23] offset1:2
	global_load_dwordx4 v[12:15], v[24:25], off
	global_load_dwordx4 v[8:11], v[26:27], off
	s_waitcnt lgkmcnt(0)
	s_barrier
	s_cbranch_vccnz .LBB0_1021
	v_mov_b32_e32 v80, 0
	s_add_i32 s22, s75, -2
	v_mul_f32_e32 v82, 0x41800000, v146
	v_mul_f32_e32 v83, 0x42000000, v146
	v_mul_f32_e32 v84, 0x42400000, v146
	v_mul_f32_e32 v85, 0, v146
	s_waitcnt lgkmcnt(7)
	v_mul_f32_e32 v86, 0x43800000, v146
	v_mul_f32_e32 v87, 0x44000000, v146
	v_mul_f32_e32 v88, 0x44400000, v146
	v_add_u32_e32 v89, s74, v169
	s_mov_b32 s24, 5
	s_movk_i32 s23, 0xc0
	v_mov_b32_e32 v81, 0
	v_mov_b32_e32 v64, 0
	v_mov_b32_e32 v65, v80
	v_mov_b32_e32 v66, v80
	v_mov_b32_e32 v67, v80
	v_mov_b32_e32 v68, 0
	v_mov_b32_e32 v69, v80
	v_mov_b32_e32 v70, v80
	v_mov_b32_e32 v71, v80
	v_mov_b32_e32 v76, 0
	v_mov_b32_e32 v77, v80
	v_mov_b32_e32 v78, v80
	v_mov_b32_e32 v79, v80
	v_mov_b32_e32 v72, 0
	v_mov_b32_e32 v73, v80
	v_mov_b32_e32 v74, v80
	v_mov_b32_e32 v75, v80

.LBB0_1059:
	s_lshl_b32 s0, s80, 1
	s_add_u32 s0, s57, s0
	s_addc_u32 s1, s60, 0
	s_add_i32 s20, s74, 0xfffffe01
	s_andn2_b32 s20, s20, 63
	s_cmp_gt_i32 s75, 31
	s_cselect_b32 s20, s20, 0
	s_sub_i32 s21, s74, s20
	s_ashr_i32 s21, s21, 6
	s_min_i32 s22, s21, 0
	s_lshl_b32 s22, s22, 6
	s_add_i32 s22, s22, s20
	s_ashr_i32 s23, s22, 31
	s_lshl_b64 s[26:27], s[22:23], 12
	s_add_u32 s26, s24, s26
	s_addc_u32 s27, s25, s27
	s_lshl_b64 s[22:23], s[22:23], 1
	s_add_u32 s22, s0, s22
	s_addc_u32 s23, s1, s23
	v_mov_b32_e32 v141, v123
	s_waitcnt vmcnt(2)
	v_lshl_add_u64 v[18:19], s[22:23], 0, v[140:141]
	s_min_i32 s22, s21, 1
	s_lshl_b32 s22, s22, 6
	s_add_i32 s22, s22, s20
	v_mov_b32_e32 v139, v123
	s_ashr_i32 s23, s22, 31
	v_lshl_add_u64 v[16:17], s[26:27], 0, v[138:139]
	s_lshl_b64 s[26:27], s[22:23], 12
	s_add_u32 s26, s24, s26
	s_addc_u32 s27, s25, s27
	s_lshl_b64 s[22:23], s[22:23], 1
	s_add_u32 s22, s0, s22
	s_addc_u32 s23, s1, s23
	v_lshl_add_u64 v[16:17], v[16:17], 0, v[122:123]
	v_lshl_add_u64 v[20:21], v[18:19], 0, v[122:123]
	s_waitcnt vmcnt(0)
	v_lshl_add_u64 v[24:25], s[26:27], 0, v[138:139]
	v_lshl_add_u64 v[26:27], s[22:23], 0, v[140:141]
	v_mov_b32_e32 v16, v240
	v_mov_b32_e32 v17, v241
	v_mov_b32_e32 v18, v242
	v_mov_b32_e32 v19, v243
	s_nop 0
	v_mov_b32_e32 v20, v244
	v_mov_b32_e32 v21, v245
	v_mov_b32_e32 v22, v246
	v_mov_b32_e32 v23, v247
	v_lshl_add_u64 v[24:25], v[24:25], 0, v[122:123]
	v_lshl_add_u64 v[28:29], v[26:27], 0, v[122:123]
	v_mov_b32_e32 v24, v248
	v_mov_b32_e32 v25, v249
	v_mov_b32_e32 v26, v250
	v_mov_b32_e32 v27, v251
	s_nop 0
	v_mov_b32_e32 v28, v252
	v_mov_b32_e32 v29, v253
	v_mov_b32_e32 v30, v254
	v_mov_b32_e32 v31, v255
	s_min_i32 s22, s21, 2
	s_lshl_b32 s22, s22, 6
	s_add_i32 s22, s22, s20
	s_ashr_i32 s23, s22, 31
	s_lshl_b64 s[26:27], s[22:23], 12
	s_add_u32 s26, s24, s26
	s_addc_u32 s27, s25, s27
	s_lshl_b64 s[22:23], s[22:23], 1
	s_add_u32 s22, s0, s22
	s_waitcnt lgkmcnt(3)
	v_lshl_add_u64 v[32:33], s[26:27], 0, v[138:139]
	s_addc_u32 s23, s1, s23
	s_min_i32 s26, s21, 3
	v_lshl_add_u64 v[34:35], s[22:23], 0, v[140:141]
	s_lshl_b32 s22, s26, 6
	s_add_i32 s22, s22, s20
	s_ashr_i32 s23, s22, 31
	s_lshl_b64 s[26:27], s[22:23], 12
	s_add_u32 s24, s24, s26
	s_addc_u32 s25, s25, s27
	s_lshl_b64 s[22:23], s[22:23], 1
	s_add_u32 s22, s0, s22
	v_lshl_add_u64 v[32:33], v[32:33], 0, v[122:123]
	v_lshl_add_u64 v[34:35], v[34:35], 0, v[122:123]
	s_addc_u32 s23, s1, s23
	s_waitcnt lgkmcnt(2)
	global_load_dwordx4 v[36:39], v[32:33], off offset:3072
	s_nop 0
	global_load_dwordx4 v[32:35], v[34:35], off
	s_waitcnt lgkmcnt(1)
	v_lshl_add_u64 v[40:41], s[24:25], 0, v[138:139]
	v_lshl_add_u64 v[42:43], s[22:23], 0, v[140:141]
	v_lshl_add_u64 v[40:41], v[40:41], 0, v[122:123]
	v_lshl_add_u64 v[42:43], v[42:43], 0, v[122:123]
	s_mov_b32 s23, 0
	s_cmp_lt_i32 s21, 1
	s_mov_b32 s24, 0
	s_waitcnt vmcnt(5)
	ds_write_b128 v151, v[16:19]
	s_waitcnt vmcnt(4)
	ds_write2_b64 v187, v[20:21], v[22:23] offset1:2
	s_waitcnt vmcnt(3)
	ds_write_b128 v151, v[24:27] offset:10240
	s_waitcnt vmcnt(2)
	ds_write2_b64 v186, v[28:29], v[30:31] offset1:2
	s_waitcnt lgkmcnt(4)
	global_load_dwordx4 v[44:47], v[40:41], off offset:3072
	s_nop 0
	global_load_dwordx4 v[40:43], v[42:43], off
	s_cselect_b32 s91, 1, 0
	s_add_i32 s98, s90, -1
	s_ashr_i32 s98, s98, 6
	s_cmp_gt_i32 s98, 0
	s_cselect_b32 s99, 0x2000, 0
	s_cselect_b32 s98, 0x80, 0
	s_and_b32 s29, s73, 3
	s_lshl_b32 s29, s29, 1
	s_bfe_u32 s30, s73, 0x10002
	s_or_b32 s29, s29, s30
	s_bfe_u32 s30, s73, 0x1000a
	s_xor_b32 s29, s29, s30
	s_lshl_b32 s29, s29, 16
	s_add_u32 s100, s3, s29
	s_addc_u32 s101, s52, 0
	s_add_u32 s30, s53, s29
	s_addc_u32 s31, s54, 0
	v_mov_b32_e32 v194, v134
	v_mov_b32_e32 v195, 0
	v_mov_b32_e32 v196, v136
	v_mov_b32_e32 v197, 0
	v_lshl_add_u64 v[198:199], s[100:101], 0, v[194:195]
	v_lshl_add_u64 v[200:201], s[30:31], 0, v[196:197]
	v_lshl_add_u64 v[198:199], v[198:199], 0, v[122:123]
	v_lshl_add_u64 v[200:201], v[200:201], 0, v[122:123]
	global_load_dwordx4 v[240:243], v[198:199], off
	global_load_dwordx4 v[244:247], v[200:201], off
	s_add_u32 s100, s100, s99
	s_addc_u32 s101, s101, 0
	s_add_u32 s30, s30, s98
	s_addc_u32 s31, s31, 0
	v_lshl_add_u64 v[198:199], s[100:101], 0, v[194:195]
	v_lshl_add_u64 v[200:201], s[30:31], 0, v[196:197]
	v_lshl_add_u64 v[198:199], v[198:199], 0, v[122:123]
	v_lshl_add_u64 v[200:201], v[200:201], 0, v[122:123]
	global_load_dwordx4 v[248:251], v[198:199], off
	global_load_dwordx4 v[252:255], v[200:201], off
	s_cmp_lg_u32 s91, 0
	s_waitcnt lgkmcnt(0)
	s_barrier
	s_cbranch_scc1 .LBB0_1068
	v_lshl_add_u64 v[16:17], s[0:1], 0, v[140:141]
	v_lshl_add_u64 v[106:107], v[16:17], 0, v[122:123]
	v_add_u32_e32 v16, s74, v171
	v_mov_b32_e32 v86, 0
	s_add_i32 s22, s74, 0xfffffe10
	v_subrev_u32_e32 v81, s20, v16
	v_mov_b32_e32 v87, v86
	v_mov_b32_e32 v88, v86
	v_mov_b32_e32 v89, v86
	s_mov_b32 s23, 5
	v_mov_b32_e32 v90, v86
	v_mov_b32_e32 v91, v86
	v_mov_b32_e32 v92, v86
	v_mov_b32_e32 v93, v86
	v_mov_b32_e32 v94, v86
	v_mov_b32_e32 v95, v86
	v_mov_b32_e32 v96, v86
	v_mov_b32_e32 v97, v86
	v_mov_b32_e32 v98, v86
	v_mov_b32_e32 v99, v86
	v_mov_b32_e32 v100, v86
	v_mov_b32_e32 v101, v86
	v_mov_b32_e32 v102, v86
	v_mov_b32_e32 v103, v86
	v_mov_b32_e32 v104, v86
	v_mov_b32_e32 v105, v86
